# grid barrier: XCD leader bumps its XCD generation word before its own invalidate instead of after (other workgroups released one atomic-ack earlier)
# speedup vs baseline: 1.0076x; 1.0076x over previous
; __device__ __forceinline__ unsigned xb_ld(unsigned* p)              { return __hip_atomic_load(p, __ATOMIC_RELAXED, __HIP_MEMORY_SCOPE_AGENT); }
; __device__ __forceinline__ unsigned xb_add(unsigned* p, unsigned v) { return __hip_atomic_fetch_add(p, v, __ATOMIC_RELAXED, __HIP_MEMORY_SCOPE_AGENT); }
; #define XB_SPIN(cond, bar) do { unsigned _sp = 0; while (cond) { __builtin_amdgcn_s_sleep(1); \
;     if ((++_sp & 255u) == 0u) { if (xb_ld(&(bar)[XB_TMO])) break; if (_sp > XB_SPIN_CAP) { atomicAdd(&(bar)[XB_TMO], 1u); break; } } } } while (0)
; __device__ __forceinline__ void xcd_barrier(unsigned* bar, unsigned x, volatile LAS unsigned* st) {
;     ...
;             __builtin_amdgcn_fence(__ATOMIC_ACQUIRE, "agent");
;             xb_add(&bar[XB_XGEN(x)], 1u);
;             asm volatile("s_waitcnt vmcnt(0)" ::: "memory");
;         } else {
;             XB_SPIN(xb_ld(&bar[XB_XGEN(x)]) == gen, bar);
;             __builtin_amdgcn_fence(__ATOMIC_ACQUIRE, "agent");
;             asm volatile("s_waitcnt vmcnt(0)" ::: "memory");
;         }
;     }
;     __syncthreads();
.LBB0_895:
	s_or_b64 exec, exec, s[6:7]
	s_mov_b64 s[6:7], exec
	v_mbcnt_lo_u32_b32 v0, s6, 0
	v_mbcnt_hi_u32_b32 v0, s7, v0
	v_cmp_eq_u32_e32 vcc, 0, v0
	s_and_saveexec_b64 s[8:9], vcc
	s_cbranch_execz .LBB0_897
	s_bcnt1_i32_b64 s2, s[6:7]
	v_mov_b32_e32 v0, s2
	global_atomic_add v194, v0, s[4:5] offset:1024
.LBB0_897:
	s_or_b64 exec, exec, s[8:9]
	s_waitcnt vmcnt(0)
	buffer_inv sc1
	s_waitcnt vmcnt(0)
.LBB0_898:
	s_or_b64 exec, exec, s[0:1]
	s_waitcnt lgkmcnt(0)
	s_barrier
	s_add_i32 s33, s33, 1
	s_cmp_eq_u32 s33, 30
	s_cbranch_scc0 .LBB0_92
	s_branch .LBB0_938
